# FFN rms-norm row loop: the 8 modulation-vector loads of a row issued together during the row-sum reduction instead of four load-wait rounds (on top of v33)
# speedup vs baseline: 1.0119x; 1.0088x over previous
.LBB0_1101:
	s_waitcnt vmcnt(3)
	v_mul_f32_e32 v0, v31, v31
	s_waitcnt vmcnt(2)
	v_mul_f32_e32 v40, v27, v27
	v_fmac_f32_e32 v0, v30, v30
	v_fmac_f32_e32 v40, v26, v26
	v_fmac_f32_e32 v0, v32, v32
	v_fmac_f32_e32 v40, v28, v28
	v_fmac_f32_e32 v0, v33, v33
	v_fmac_f32_e32 v40, v29, v29
	s_waitcnt vmcnt(0)
	v_pk_mul_f32 v[54:55], v[18:19], v[18:19]
	v_pk_mul_f32 v[56:57], v[22:23], v[22:23]
	v_add_f32_e32 v0, v0, v40
	v_pk_mul_f32 v[40:41], v[20:21], v[20:21]
	v_pk_mul_f32 v[52:53], v[24:25], v[24:25]
	v_mov_b32_e32 v58, v54
	v_mov_b32_e32 v59, v56
	v_mov_b32_e32 v56, v55
	v_pk_add_f32 v[54:55], v[58:59], v[56:57]
	v_mov_b32_e32 v56, v40
	v_mov_b32_e32 v57, v52
	v_pk_add_f32 v[54:55], v[56:57], v[54:55]
	v_mov_b32_e32 v52, v41
	v_pk_add_f32 v[40:41], v[52:53], v[54:55]
	s_cmpk_lt_u32 s6, 0x4000
	v_add_f32_e32 v0, v41, v0
	v_add_f32_e32 v0, v40, v0
	ds_bpermute_b32 v40, v42, v0
	s_movk_i32 s5, 0x4800
	s_cselect_b32 s5, 0x2400, s5
	s_cmpk_gt_i32 s6, 0x1fff
	s_cselect_b32 s5, s5, 0
	s_waitcnt lgkmcnt(0)
	v_add_f32_e32 v0, v0, v40
	ds_bpermute_b32 v40, v43, v0
	s_lshl_b32 s5, s5, 2
	s_add_u32 s8, s0, s5
	s_addc_u32 s9, s1, 0
	s_add_u32 s10, s8, 0x1000
	s_waitcnt lgkmcnt(0)
	v_add_f32_e32 v0, v0, v40
	ds_bpermute_b32 v40, v44, v0
	s_addc_u32 s11, s9, 0
	global_load_dwordx4 v[60:63], v48, s[10:11]
	global_load_dwordx4 v[64:67], v48, s[8:9]
	global_load_dwordx4 v[68:71], v49, s[10:11]
	global_load_dwordx4 v[72:75], v48, s[8:9] offset:1024
	global_load_dwordx4 v[76:79], v50, s[10:11]
	global_load_dwordx4 v[80:83], v48, s[8:9] offset:2048
	global_load_dwordx4 v[84:87], v51, s[10:11]
	global_load_dwordx4 v[88:91], v48, s[8:9] offset:3072
	s_waitcnt lgkmcnt(0)
	v_add_f32_e32 v0, v0, v40
	ds_bpermute_b32 v40, v45, v0
	s_waitcnt lgkmcnt(0)
	v_add_f32_e32 v0, v0, v40
	ds_bpermute_b32 v40, v46, v0
	s_waitcnt lgkmcnt(0)
	v_add_f32_e32 v0, v0, v40
	ds_bpermute_b32 v40, v47, v0
	s_waitcnt lgkmcnt(0)
	v_add_f32_e32 v0, v0, v40
	v_fmamk_f32 v0, v0, 0x3a800000, v199
	v_cmp_gt_f32_e32 vcc, s21, v0
	v_mul_f32_e32 v40, 0x4f800000, v0
	s_nop 0
	v_cndmask_b32_e32 v0, v0, v40, vcc
	v_sqrt_f32_e32 v40, v0
	s_nop 0
	v_add_u32_e32 v41, -1, v40
	v_fma_f32 v52, -v41, v40, v0
	v_cmp_ge_f32_e64 s[38:39], 0, v52
	v_add_u32_e32 v52, 1, v40
	s_nop 0
	v_cndmask_b32_e64 v41, v40, v41, s[38:39]
	v_fma_f32 v40, -v52, v40, v0
	v_cmp_lt_f32_e64 s[38:39], 0, v40
	s_nop 1
	v_cndmask_b32_e64 v40, v41, v52, s[38:39]
	v_mul_f32_e32 v41, 0x37800000, v40
	v_cndmask_b32_e32 v40, v40, v41, vcc
	v_cmp_class_f32_e32 vcc, v0, v200
	s_nop 1
	v_cndmask_b32_e32 v0, v40, v0, vcc
	v_div_scale_f32 v40, s[16:17], v0, v0, 1.0
	v_rcp_f32_e32 v41, v40
	s_lshl_b64 s[16:17], s[6:7], 11
	v_fma_f32 v52, -v40, v41, 1.0
	v_fmac_f32_e32 v41, v52, v41
	v_div_scale_f32 v52, vcc, 1.0, v0, 1.0
	v_mul_f32_e32 v53, v52, v41
	v_fma_f32 v54, -v40, v53, v52
	v_fmac_f32_e32 v53, v54, v41
	v_fma_f32 v40, -v40, v53, v52
	v_div_fmas_f32 v40, v40, v41, v53
	v_div_fixup_f32 v0, v40, v0, 1.0
	v_pk_mul_f32 v[30:31], v[30:31], v[0:1] op_sel_hi:[1,0]
	v_pk_mul_f32 v[32:33], v[32:33], v[0:1] op_sel_hi:[1,0]
	v_pk_mul_f32 v[30:31], v[2:3], v[30:31]
	v_pk_mul_f32 v[32:33], v[4:5], v[32:33]
	v_pk_mul_f32 v[26:27], v[26:27], v[0:1] op_sel_hi:[1,0]
	v_pk_mul_f32 v[28:29], v[28:29], v[0:1] op_sel_hi:[1,0]
	v_pk_mul_f32 v[26:27], v[6:7], v[26:27]
	v_pk_mul_f32 v[28:29], v[8:9], v[28:29]
	v_pk_mul_f32 v[22:23], v[22:23], v[0:1] op_sel_hi:[1,0]
	v_pk_mul_f32 v[24:25], v[24:25], v[0:1] op_sel_hi:[1,0]
	v_pk_mul_f32 v[22:23], v[10:11], v[22:23]
	v_pk_mul_f32 v[24:25], v[12:13], v[24:25]
	v_pk_mul_f32 v[18:19], v[18:19], v[0:1] op_sel_hi:[1,0]
	v_pk_mul_f32 v[20:21], v[20:21], v[0:1] op_sel_hi:[1,0]
	v_pk_mul_f32 v[18:19], v[18:19], v[14:15]
	v_pk_mul_f32 v[20:21], v[20:21], v[16:17]
	s_waitcnt vmcnt(0)
	v_pk_add_f32 v[40:41], v[60:61], 1.0 op_sel_hi:[1,0]
	s_nop 0
	v_pk_fma_f32 v[30:31], v[40:41], v[30:31], v[64:65]
	v_pk_add_f32 v[40:41], v[62:63], 1.0 op_sel_hi:[1,0]
	s_nop 0
	v_pk_fma_f32 v[32:33], v[40:41], v[32:33], v[66:67]
	v_cvt_pk_bf16_f32 v40, v30, v31
	v_cvt_pk_bf16_f32 v41, v32, v33
	v_lshl_add_u64 v[30:31], v[36:37], 0, s[16:17]
	global_store_dwordx2 v[30:31], v[40:41], off
	v_pk_add_f32 v[32:33], v[68:69], 1.0 op_sel_hi:[1,0]
	s_nop 0
	v_pk_fma_f32 v[26:27], v[32:33], v[26:27], v[72:73]
	v_pk_add_f32 v[32:33], v[70:71], 1.0 op_sel_hi:[1,0]
	v_cvt_pk_bf16_f32 v26, v26, v27
	v_pk_fma_f32 v[28:29], v[32:33], v[28:29], v[74:75]
	s_nop 0
	v_cvt_pk_bf16_f32 v27, v28, v29
	global_store_dwordx2 v[30:31], v[26:27], off offset:512
	v_pk_add_f32 v[26:27], v[76:77], 1.0 op_sel_hi:[1,0]
	s_nop 0
	v_pk_fma_f32 v[22:23], v[22:23], v[26:27], v[80:81]
	v_pk_add_f32 v[26:27], v[78:79], 1.0 op_sel_hi:[1,0]
	v_cvt_pk_bf16_f32 v22, v22, v23
	v_pk_fma_f32 v[24:25], v[24:25], v[26:27], v[82:83]
	s_nop 0
	v_cvt_pk_bf16_f32 v23, v24, v25
	global_store_dwordx2 v[30:31], v[22:23], off offset:1024
	v_readlane_b32 s8, v249, 52
	s_add_i32 s6, s6, s8
	s_add_i32 s4, s4, s8
	s_cmp_ge_i32 s6, s12
	v_readlane_b32 s9, v249, 53
	v_pk_add_f32 v[26:27], v[84:85], 1.0 op_sel_hi:[1,0]
	s_nop 0
	v_pk_fma_f32 v[18:19], v[18:19], v[26:27], v[88:89]
	v_pk_add_f32 v[22:23], v[86:87], 1.0 op_sel_hi:[1,0]
	v_cvt_pk_bf16_f32 v18, v18, v19
	v_pk_fma_f32 v[20:21], v[20:21], v[22:23], v[90:91]
	s_nop 0
	v_cvt_pk_bf16_f32 v19, v20, v21
	global_store_dwordx2 v[30:31], v[18:19], off offset:1536
	s_cbranch_scc1 .LBB0_1106
